# baseline (speedup 1.0000x reference)
.LBB0_176:
	v_cndmask_b32_e64 v147, 0, 1, s[52:53]
	v_cmp_ne_u32_e64 s[46:47], 1, v147
	s_andn2_b64 vcc, exec, s[52:53]
	s_cbranch_vccnz .LBB0_181
	s_waitcnt vmcnt(5) lgkmcnt(0)
	s_barrier
	s_cbranch_execz .LBB0_181

.LBB0_179:
	s_add_i32 s3, s87, s55
	s_mov_b64 s[22:23], 0x298e8000
	v_lshl_add_u64 v[150:151], v[174:175], 0, s[22:23]
	s_mov_b32 m0, s3
	s_nop 0
	global_load_lds_dwordx4 v[150:151], off
	v_lshl_add_u64 v[150:151], v[172:173], 0, s[22:23]
	s_add_i32 m0, s3, 0x2000
	s_nop 0
	global_load_lds_dwordx4 v[150:151], off
	v_lshl_add_u64 v[150:151], v[170:171], 0, s[22:23]
	s_add_i32 m0, s3, 0x4000
	s_nop 0
	global_load_lds_dwordx4 v[150:151], off
	s_and_b64 vcc, exec, s[46:47]
	s_cbranch_vccz .LBB0_183
	s_branch .LBB0_184
.LBB0_181:
	s_waitcnt vmcnt(2) lgkmcnt(0)
	s_barrier
	s_cmpk_gt_u32 s75, 0x7d
	s_cselect_b64 s[52:53], -1, 0
	s_and_b64 vcc, exec, s[52:53]
	s_cbranch_vccz .LBB0_179

; __device__ __forceinline__ int crow(int r, int hi) { return (r & 3) + 8 * (r >> 2) + 4 * hi; }
; __device__ __forceinline__ void partialSM_ref(f32x16& p0, f32x16& p1, float& m_reg, float& mn, float& alpha, float pmax) {
;     constexpr float C = SCALE * 1.4426950408889634f;
;     if (__builtin_expect(__all(pmax - m_reg <= THR / SCALE), 1)) { mn = m_reg; alpha = 1.f; }
;     else { mn = fmaxf(m_reg, pmax); alpha = __builtin_amdgcn_exp2f((m_reg - mn) * C); m_reg = mn; }
;     const float mnC = -mn * C;
; #pragma unroll
;     for (int r = 0; r < 16; ++r) p0[r] = fmaf(p0[r], C, mnC);
; #pragma unroll
;     for (int r = 0; r < 16; ++r) p1[r] = fmaf(p1[r], C, mnC);
; #pragma unroll
;     for (int r = 0; r < 16; ++r) p0[r] = __builtin_amdgcn_exp2f(p0[r]);
; __device__ __forceinline__ void kmask(f32x16& p0, f32x16& p1, int tile, int hi) {
;     if (tile * KVBLK + KVBLK > T_) {
; #pragma unroll
;         for (int r = 0; r < 16; ++r) { const int key = tile * KVBLK + crow(r, hi); if (key >= T_) p0[r] = -1e30f; if (key + 32 >= T_) p1[r] = -1e30f; }
;     }
.LBB0_188:
	v_cndmask_b32_e64 v230, v145, v146, s[48:49]
	v_cndmask_b32_e64 v95, v95, v198, s[44:45]
	v_cndmask_b32_e64 v94, v94, v198, s[44:45]
	v_cndmask_b32_e64 v93, v93, v198, s[44:45]
	v_cndmask_b32_e64 v92, v92, v198, s[44:45]
	v_cndmask_b32_e64 v91, v91, v198, s[44:45]
	v_cndmask_b32_e64 v90, v90, v198, s[44:45]
	v_cndmask_b32_e64 v89, v89, v198, s[44:45]
	v_cndmask_b32_e64 v150, v88, v198, s[44:45]
	v_mul_f32_e32 v88, 0xbdd53b94, v230
	v_fmamk_f32 v80, v80, 0x3dd53b94, v88
	v_fmamk_f32 v81, v81, 0x3dd53b94, v88
	v_fmamk_f32 v82, v82, 0x3dd53b94, v88
	v_fmamk_f32 v83, v83, 0x3dd53b94, v88
	v_fmamk_f32 v84, v84, 0x3dd53b94, v88
	v_fmamk_f32 v85, v85, 0x3dd53b94, v88
	v_fmamk_f32 v86, v86, 0x3dd53b94, v88
	v_fmamk_f32 v87, v87, 0x3dd53b94, v88
	v_fmamk_f32 v145, v150, 0x3dd53b94, v88
	v_fmamk_f32 v89, v89, 0x3dd53b94, v88
	v_fmamk_f32 v90, v90, 0x3dd53b94, v88
	v_fmamk_f32 v91, v91, 0x3dd53b94, v88
	v_fmamk_f32 v92, v92, 0x3dd53b94, v88
	v_fmamk_f32 v93, v93, 0x3dd53b94, v88
	v_fmamk_f32 v94, v94, 0x3dd53b94, v88
	v_fmamk_f32 v95, v95, 0x3dd53b94, v88
	v_exp_f32_e32 v244, v80
	v_exp_f32_e32 v246, v81
	v_exp_f32_e32 v242, v82
	v_exp_f32_e32 v245, v83
	v_exp_f32_e32 v241, v84
	v_exp_f32_e32 v243, v85
	v_exp_f32_e32 v239, v86
	v_exp_f32_e32 v240, v87
	v_exp_f32_e32 v236, v145
	v_exp_f32_e32 v238, v89
	v_exp_f32_e32 v235, v90
	v_exp_f32_e32 v237, v91
	v_exp_f32_e32 v232, v92
	v_exp_f32_e32 v234, v93
	v_exp_f32_e32 v231, v94
	v_exp_f32_e32 v233, v95
	s_and_b64 vcc, exec, s[52:53]
	s_cbranch_vccnz .Lattn_rare
	s_waitcnt vmcnt(5) lgkmcnt(0)
	s_barrier

.Lattn_rare:
	s_and_b64 vcc, exec, s[46:47]
	s_cbranch_vccnz .Lattn_rare0
	s_waitcnt vmcnt(2) lgkmcnt(0)
	s_barrier
	s_branch .LBB0_196
.Lattn_rare0:
	s_waitcnt vmcnt(0) lgkmcnt(0)
	s_barrier
	s_branch .LBB0_196
